# grid barrier poll: 16 counter loads issued back to back, one wait, then the sum (was a load-wait-add ladder), all 10 barriers
# speedup vs baseline: 1.0093x; 1.0093x over previous
; __device__ __forceinline__ unsigned xb_ld(unsigned* p)              { return __hip_atomic_load(p, __ATOMIC_RELAXED, __HIP_MEMORY_SCOPE_AGENT); }
; __device__ __forceinline__ void xcd_barrier_complete(unsigned* bar, unsigned x, unsigned& nloc, unsigned& nx) {
;     const unsigned G = gridDim.x * gridDim.y * gridDim.z;
;     unsigned sum, cnt, mine, sp = 0u;
;     for (;;) {
;         sum = 0u; cnt = 0u; mine = 0u;
; #pragma unroll
;         for (unsigned j = 0; j < 16; ++j) { const unsigned c = xb_ld(&bar[XB_XCNT(j)]); sum += c; cnt += (c > 0u) ? 1u : 0u; mine = (j == x) ? c : mine; }
;         if (sum == G) break;
;         __builtin_amdgcn_s_sleep(1);
;         if ((++sp & 255u) == 0u) { if (xb_ld(&bar[XB_TMO])) break; if (sp > XB_SPIN_CAP) { atomicAdd(&bar[XB_TMO], 1u); break; } }
;     }
.LBB0_159:
	v_readlane_b32 s2, v253, 8
	v_readlane_b32 s3, v253, 9
	s_nop 4
	global_load_dword v4, v1, s[18:19] sc1
	global_load_dword v0, v1, s[28:29] sc1
	s_waitcnt lgkmcnt(0)
	global_load_dword v2, v1, s[48:49] sc1
	global_load_dword v3, v1, s[50:51] sc1
	s_mov_b64 s[4:5], -1
	global_load_dword v5, v1, s[2:3] sc1
	v_readlane_b32 s2, v253, 10
	v_readlane_b32 s3, v253, 11
	s_nop 4
	global_load_dword v6, v1, s[2:3] sc1
	v_readlane_b32 s2, v253, 12
	v_readlane_b32 s3, v253, 13
	s_nop 4
	global_load_dword v7, v1, s[2:3] sc1
	v_readlane_b32 s2, v253, 14
	v_readlane_b32 s3, v253, 15
	s_nop 4
	global_load_dword v8, v1, s[2:3] sc1
	v_readlane_b32 s2, v253, 16
	v_readlane_b32 s3, v253, 17
	s_nop 4
	global_load_dword v9, v1, s[2:3] sc1
	v_readlane_b32 s2, v253, 18
	v_readlane_b32 s3, v253, 19
	s_nop 4
	global_load_dword v10, v1, s[2:3] sc1
	v_readlane_b32 s2, v253, 20
	v_readlane_b32 s3, v253, 21
	s_nop 4
	global_load_dword v11, v1, s[2:3] sc1
	v_readlane_b32 s2, v253, 22
	v_readlane_b32 s3, v253, 23
	s_nop 4
	global_load_dword v12, v1, s[2:3] sc1
	v_readlane_b32 s2, v253, 24
	v_readlane_b32 s3, v253, 25
	s_nop 4
	global_load_dword v13, v1, s[2:3] sc1
	v_readlane_b32 s2, v253, 26
	v_readlane_b32 s3, v253, 27
	s_nop 4
	global_load_dword v14, v1, s[2:3] sc1
	v_readlane_b32 s2, v253, 28
	v_readlane_b32 s3, v253, 29
	s_nop 4
	global_load_dword v15, v1, s[2:3] sc1
	v_readlane_b32 s2, v253, 30
	v_readlane_b32 s3, v253, 31
	s_nop 4
	global_load_dword v16, v1, s[2:3] sc1
	s_mov_b64 s[2:3], -1
	s_waitcnt vmcnt(0)
	v_add_u32_e32 v17, v0, v4
	v_add_u32_e32 v17, v17, v2
	v_add_u32_e32 v17, v17, v3
	v_add_u32_e32 v17, v17, v5
	v_add_u32_e32 v17, v17, v6
	v_add_u32_e32 v17, v17, v7
	v_add_u32_e32 v17, v17, v8
	v_add_u32_e32 v17, v17, v9
	v_add_u32_e32 v17, v17, v10
	v_add_u32_e32 v17, v17, v11
	v_add_u32_e32 v17, v17, v12
	v_add_u32_e32 v17, v17, v13
	v_add_u32_e32 v17, v17, v14
	v_add_u32_e32 v17, v17, v15
	v_add_u32_e32 v17, v17, v16
	v_cmp_eq_u32_e32 vcc, s25, v17
	s_cbranch_vccnz .LBB0_158
	s_and_b32 s2, s8, 0xff
	s_cmp_eq_u32 s2, 0
	s_mov_b64 s[2:3], -1
	s_mov_b64 s[6:7], -1
	s_sleep 1
	s_cbranch_scc1 .LBB0_163
	s_and_b64 vcc, exec, s[6:7]
	s_cbranch_vccz .LBB0_158

; __device__ __forceinline__ unsigned xb_ld(unsigned* p)              { return __hip_atomic_load(p, __ATOMIC_RELAXED, __HIP_MEMORY_SCOPE_AGENT); }
; __device__ __forceinline__ void xcd_barrier_complete(unsigned* bar, unsigned x, unsigned& nloc, unsigned& nx) {
;     ...
;     for (;;) {
;         sum = 0u; cnt = 0u; mine = 0u;
; #pragma unroll
;         for (unsigned j = 0; j < 16; ++j) { const unsigned c = xb_ld(&bar[XB_XCNT(j)]); sum += c; cnt += (c > 0u) ? 1u : 0u; mine = (j == x) ? c : mine; }
;         if (sum == G) break;
;         __builtin_amdgcn_s_sleep(1);
;         if ((++sp & 255u) == 0u) { if (xb_ld(&bar[XB_TMO])) break; if (sp > XB_SPIN_CAP) { atomicAdd(&bar[XB_TMO], 1u); break; } }
;     }
.LBB0_380:
	v_readlane_b32 s2, v253, 8
	v_readlane_b32 s3, v253, 9
	s_nop 4
	global_load_dword v4, v1, s[10:11] sc1
	global_load_dword v0, v1, s[28:29] sc1
	s_waitcnt lgkmcnt(0)
	global_load_dword v2, v1, s[48:49] sc1
	global_load_dword v3, v1, s[50:51] sc1
	s_mov_b64 s[4:5], -1
	global_load_dword v5, v1, s[2:3] sc1
	v_readlane_b32 s2, v253, 10
	v_readlane_b32 s3, v253, 11
	s_nop 4
	global_load_dword v6, v1, s[2:3] sc1
	v_readlane_b32 s2, v253, 12
	v_readlane_b32 s3, v253, 13
	s_nop 4
	global_load_dword v7, v1, s[2:3] sc1
	v_readlane_b32 s2, v253, 14
	v_readlane_b32 s3, v253, 15
	s_nop 4
	global_load_dword v8, v1, s[2:3] sc1
	v_readlane_b32 s2, v253, 16
	v_readlane_b32 s3, v253, 17
	s_nop 4
	global_load_dword v9, v1, s[2:3] sc1
	v_readlane_b32 s2, v253, 18
	v_readlane_b32 s3, v253, 19
	s_nop 4
	global_load_dword v10, v1, s[2:3] sc1
	v_readlane_b32 s2, v253, 20
	v_readlane_b32 s3, v253, 21
	s_nop 4
	global_load_dword v11, v1, s[2:3] sc1
	v_readlane_b32 s2, v253, 22
	v_readlane_b32 s3, v253, 23
	s_nop 4
	global_load_dword v12, v1, s[2:3] sc1
	v_readlane_b32 s2, v253, 24
	v_readlane_b32 s3, v253, 25
	s_nop 4
	global_load_dword v13, v1, s[2:3] sc1
	v_readlane_b32 s2, v253, 26
	v_readlane_b32 s3, v253, 27
	s_nop 4
	global_load_dword v14, v1, s[2:3] sc1
	v_readlane_b32 s2, v253, 28
	v_readlane_b32 s3, v253, 29
	s_nop 4
	global_load_dword v15, v1, s[2:3] sc1
	v_readlane_b32 s2, v253, 30
	v_readlane_b32 s3, v253, 31
	s_nop 4
	global_load_dword v16, v1, s[2:3] sc1
	s_mov_b64 s[2:3], -1
	s_waitcnt vmcnt(0)
	v_add_u32_e32 v17, v0, v4
	v_add_u32_e32 v17, v17, v2
	v_add_u32_e32 v17, v17, v3
	v_add_u32_e32 v17, v17, v5
	v_add_u32_e32 v17, v17, v6
	v_add_u32_e32 v17, v17, v7
	v_add_u32_e32 v17, v17, v8
	v_add_u32_e32 v17, v17, v9
	v_add_u32_e32 v17, v17, v10
	v_add_u32_e32 v17, v17, v11
	v_add_u32_e32 v17, v17, v12
	v_add_u32_e32 v17, v17, v13
	v_add_u32_e32 v17, v17, v14
	v_add_u32_e32 v17, v17, v15
	v_add_u32_e32 v17, v17, v16
	v_cmp_eq_u32_e32 vcc, s25, v17
	s_cbranch_vccnz .LBB0_379
	s_and_b32 s2, s8, 0xff
	s_cmp_eq_u32 s2, 0
	s_mov_b64 s[2:3], -1
	s_mov_b64 s[6:7], -1
	s_sleep 1
	s_cbranch_scc1 .LBB0_384
	s_and_b64 vcc, exec, s[6:7]
	s_cbranch_vccz .LBB0_379
